# residual epilogue of the out-projection and down-projection: all residual loads of a tile requested up front (re-test on the aligned K-loops)
# speedup vs baseline: 1.0106x; 1.0027x over previous
; #define PG8_STAGEA(bufoff, gbase, voff) PG8_STAGE_X(bufoff, gbase, voff, AUXA)
; #define PG8_STAGEB(bufoff, gbase, voff) PG8_STAGE_X(bufoff, gbase, voff, AUXB)
; #define PG8_LDA(dst, b, h) do { _Pragma("unroll") for (int m = 0; m < 4; ++m) _Pragma("unroll") for (int k = 0; k < 2; ++k) dst[m][k] = *(const PG8_LAS bf16x8*)(lds + PG8_SA(b, h) + aoff + m * 2048 + k * 1024); } while (0)
; #define PG8_LDB(dst, b, h) do { _Pragma("unroll") for (int n = 0; n < 2; ++n) _Pragma("unroll") for (int k = 0; k < 2; ++k) dst[n][k] = *(const PG8_LAS bf16x8*)(lds + PG8_SB(b, h) + boff + n * 2048 + k * 1024); } while (0)
; #define PG8_MMA(ai, bj, At, Bt) do { if (GEMM_PRIO_MODE == 0) __builtin_amdgcn_s_setprio(1); PG8_MMA_LOOPS \
;         acc[ai][bj][m][n] = __builtin_amdgcn_mfma_f32_16x16x32_bf16(Bt[n][k], At[m][k], acc[ai][bj][m][n], 0, 0, 0); if (GEMM_PRIO_MODE == 0) __builtin_amdgcn_s_setprio(0); } while (0)
; #define PG8_WAIT_V(n) asm volatile("s_waitcnt vmcnt(" #n ")" ::: "memory")
; #define PG8_WAIT_L(n) asm volatile("s_waitcnt lgkmcnt(" #n ")" ::: "memory")
; #define PG8_BAR __builtin_amdgcn_s_barrier()
; #define PG8_SCHED __builtin_amdgcn_sched_barrier(0)
;     ...
;         for (int t = t0; t < nt; t += 2) {
;             const bool last = (t == nt - 2);
;             const char* a1 = cA + (size_t)(t + 1) * kstepA;
;             const char* a2 = last ? nA : cA + (size_t)(t + 2) * kstepA; const char* b2 = last ? nB : cB + (size_t)(t + 2) * kstepB;
;             const char* a3 = a2 + kstepA; const char* b3 = b2 + kstepB;
;             if (last && has_next) S.a_ready(nxt);
;             if constexpr (SP2) {
;             PG8_LDB(B0, 0, 0); PG8_LDB(B1, 0, 1); PG8_SCHED; PG8_LDA(At, 0, 0); PG8_STAGEA(PG8_SA(1, 1), a1 + hstepA, voffA);
;     ...
;             const int relax = __builtin_amdgcn_readfirstlane((t == 0 && ui > 0) ? 1 : 0);
;             PG8_WAIT_VR(8, 24, relax); PG8_WAIT_L(0); PG8_BAR; PG8_MMA(0, 0, At, B0); PG8_MMA(0, 1, At, B1); PG8_BAR; PG8_SCHED;
;     ...
;             PG8_WAIT_V(8); PG8_WAIT_L(0); PG8_BAR; PG8_MMA(0, 0, At, B0); PG8_MMA(0, 1, At, B1); PG8_BAR; PG8_SCHED;
;     ...
;             PG8_LDA(At, 0, 1); PG8_STAGEB(PG8_SB(0, 0), b2, voffB); PG8_STAGEB(PG8_SB(0, 1), b2 + hstepB, voffB); PG8_STAGEA(PG8_SA(0, 0), a2, voffA);
;     ...
;             PG8_WAIT_VR(8, 24, relax); PG8_WAIT_L(0); PG8_BAR; PG8_MMA(1, 0, At, B0); PG8_MMA(1, 1, At, B1); PG8_BAR; PG8_SCHED;
.LBB0_711:
	s_ashr_i32 s25, s24, 31
	s_lshl_b64 s[0:1], s[24:25], 21
	s_add_u32 s26, s56, s0
	s_addc_u32 s27, s57, s1
	s_and_b64 s[0:1], s[10:11], exec
	s_cselect_b32 s0, s27, s13
	s_cselect_b32 s1, s26, s12
	s_ashr_i32 s23, s22, 31
	s_lshl_b64 s[6:7], s[22:23], 21
	s_add_u32 s36, s51, s6
	s_addc_u32 s37, s68, s7
	s_and_b64 s[6:7], s[10:11], exec
	s_cselect_b32 s23, s37, s43
	s_cselect_b32 s25, s36, s42
	s_add_u32 s40, s12, 0x100080
	s_addc_u32 s41, s13, 0
	s_add_u32 s12, s42, 0x100
	s_addc_u32 s13, s43, 0
	s_mov_b32 s39, -2
	s_add_u32 s6, s40, 0xfff00080
	s_addc_u32 s7, s41, -1
	s_add_i32 s95, 0, 0x10000
	s_cmp_eq_u32 s39, 60
	s_cselect_b32 s43, s0, s7
	s_cselect_b32 s42, s1, s6
	v_add_u32_e32 v144, s95, v146
	s_cselect_b32 s17, s23, s13
	s_cselect_b32 s16, s25, s12
	s_add_i32 vcc_lo, 0, 0x14000
	ds_read_b128 v[150:153], v144
	ds_read_b128 v[154:157], v144 offset:1024
	ds_read_b128 v[158:161], v144 offset:2048
	ds_read_b128 v[162:165], v144 offset:3072
	v_add_u32_e32 v144, vcc_lo, v146
	ds_read_b128 v[166:169], v144
	ds_read_b128 v[170:173], v144 offset:1024
	ds_read_b128 v[174:177], v144 offset:2048
	ds_read_b128 v[178:181], v144 offset:3072
	v_lshl_add_u64 v[144:145], s[40:41], 0, v[140:141]
	s_add_i32 m0, s69, 0xc000
	ds_read_b128 v[182:185], v148
	ds_read_b128 v[186:189], v148 offset:1024
	ds_read_b128 v[190:193], v148 offset:2048
	ds_read_b128 v[194:197], v148 offset:3072
	ds_read_b128 v[198:201], v148 offset:4096
	ds_read_b128 v[202:205], v148 offset:5120
	ds_read_b128 v[206:209], v148 offset:6144
	ds_read_b128 v[210:213], v148 offset:7168
	global_load_lds_dwordx4 v[144:145], off
	v_lshl_add_u64 v[144:145], s[40:41], 0, v[142:143]
	s_add_i32 m0, s69, 0xe000
	s_nop 0
	global_load_lds_dwordx4 v[144:145], off
	s_waitcnt vmcnt(8)
	s_waitcnt lgkmcnt(0)
	s_nop 0
	s_nop 0
	s_nop 0
	s_setprio 1
	s_barrier
	v_mfma_f32_16x16x32_bf16 v[126:129], v[150:153], v[182:185], 0
	v_mfma_f32_16x16x32_bf16 v[122:125], v[158:161], v[182:185], 0
	v_mfma_f32_16x16x32_bf16 v[110:113], v[150:153], v[190:193], 0
	v_mfma_f32_16x16x32_bf16 v[106:109], v[158:161], v[190:193], 0
	v_mfma_f32_16x16x32_bf16 v[94:97], v[150:153], v[198:201], 0
	v_mfma_f32_16x16x32_bf16 v[90:93], v[158:161], v[198:201], 0
	v_mfma_f32_16x16x32_bf16 v[78:81], v[150:153], v[206:209], 0
	v_mfma_f32_16x16x32_bf16 v[74:77], v[158:161], v[206:209], 0
	v_mfma_f32_16x16x32_bf16 v[126:129], v[154:157], v[186:189], v[126:129]
	v_mfma_f32_16x16x32_bf16 v[122:125], v[162:165], v[186:189], v[122:125]
	v_mfma_f32_16x16x32_bf16 v[110:113], v[154:157], v[194:197], v[110:113]
	v_mfma_f32_16x16x32_bf16 v[106:109], v[162:165], v[194:197], v[106:109]
	v_mfma_f32_16x16x32_bf16 v[94:97], v[154:157], v[202:205], v[94:97]
	v_mfma_f32_16x16x32_bf16 v[90:93], v[162:165], v[202:205], v[90:93]
	v_mfma_f32_16x16x32_bf16 v[78:81], v[154:157], v[210:213], v[78:81]
	v_mfma_f32_16x16x32_bf16 v[74:77], v[162:165], v[210:213], v[74:77]
	v_mfma_f32_16x16x32_bf16 v[118:121], v[166:169], v[182:185], 0
	v_mfma_f32_16x16x32_bf16 v[114:117], v[174:177], v[182:185], 0
	v_mfma_f32_16x16x32_bf16 v[102:105], v[166:169], v[190:193], 0
	v_mfma_f32_16x16x32_bf16 v[98:101], v[174:177], v[190:193], 0
	v_mfma_f32_16x16x32_bf16 v[86:89], v[166:169], v[198:201], 0
	v_mfma_f32_16x16x32_bf16 v[82:85], v[174:177], v[198:201], 0
	v_mfma_f32_16x16x32_bf16 v[70:73], v[166:169], v[206:209], 0
	v_mfma_f32_16x16x32_bf16 v[66:69], v[174:177], v[206:209], 0
	v_mfma_f32_16x16x32_bf16 v[118:121], v[170:173], v[186:189], v[118:121]
	v_mfma_f32_16x16x32_bf16 v[114:117], v[178:181], v[186:189], v[114:117]
	v_mfma_f32_16x16x32_bf16 v[102:105], v[170:173], v[194:197], v[102:105]
	v_mfma_f32_16x16x32_bf16 v[98:101], v[178:181], v[194:197], v[98:101]
	v_mfma_f32_16x16x32_bf16 v[86:89], v[170:173], v[202:205], v[86:89]
	v_mfma_f32_16x16x32_bf16 v[82:85], v[178:181], v[202:205], v[82:85]
	v_mfma_f32_16x16x32_bf16 v[70:73], v[170:173], v[210:213], v[70:73]
	v_mfma_f32_16x16x32_bf16 v[66:69], v[178:181], v[210:213], v[66:69]
	s_barrier
	s_setprio 0
	s_add_i32 s6, s95, s50
	v_lshl_add_u64 v[144:145], s[16:17], 0, v[134:135]
	s_mov_b32 m0, s6
	ds_read_b128 v[182:185], v148 offset:16384
	ds_read_b128 v[186:189], v148 offset:17408
	ds_read_b128 v[190:193], v148 offset:18432
	ds_read_b128 v[194:197], v148 offset:19456
	ds_read_b128 v[198:201], v148 offset:20480
	ds_read_b128 v[202:205], v148 offset:21504
	ds_read_b128 v[206:209], v148 offset:22528
	ds_read_b128 v[210:213], v148 offset:23552
	global_load_lds_dwordx4 v[144:145], off
	s_add_i32 m0, s6, 0x2000
	s_add_u32 s6, s16, 0x100000
	v_lshl_add_u64 v[214:215], s[16:17], 0, v[130:131]
	s_addc_u32 s7, s17, 0
	s_add_i32 s95, vcc_lo, s50
	global_load_lds_dwordx4 v[214:215], off
	v_lshl_add_u64 v[216:217], s[6:7], 0, v[134:135]
	s_mov_b32 m0, s95
	v_lshl_add_u64 v[218:219], s[42:43], 0, v[132:133]
	global_load_lds_dwordx4 v[216:217], off
	v_lshl_add_u64 v[216:217], s[6:7], 0, v[130:131]
	s_add_i32 m0, s95, 0x2000
	s_nop 0
	global_load_lds_dwordx4 v[216:217], off
	v_lshl_add_u64 v[216:217], s[42:43], 0, v[136:137]
	s_mov_b32 m0, s69
	s_nop 0
	global_load_lds_dwordx4 v[216:217], off
	s_mov_b32 m0, s72
	s_nop 0
	global_load_lds_dwordx4 v[218:219], off
	s_waitcnt vmcnt(8)
	s_waitcnt lgkmcnt(0)
	s_nop 0
	s_nop 0
	s_setprio 1
	s_barrier
; #define PG8_STAGEA(bufoff, gbase, voff) PG8_STAGE_X(bufoff, gbase, voff, AUXA)
; #define PG8_LDA(dst, b, h) do { _Pragma("unroll") for (int m = 0; m < 4; ++m) _Pragma("unroll") for (int k = 0; k < 2; ++k) dst[m][k] = *(const PG8_LAS bf16x8*)(lds + PG8_SA(b, h) + aoff + m * 2048 + k * 1024); } while (0)
; #define PG8_LDB(dst, b, h) do { _Pragma("unroll") for (int n = 0; n < 2; ++n) _Pragma("unroll") for (int k = 0; k < 2; ++k) dst[n][k] = *(const PG8_LAS bf16x8*)(lds + PG8_SB(b, h) + boff + n * 2048 + k * 1024); } while (0)
; #define PG8_MMA(ai, bj, At, Bt) do { if (GEMM_PRIO_MODE == 0) __builtin_amdgcn_s_setprio(1); PG8_MMA_LOOPS \
;         acc[ai][bj][m][n] = __builtin_amdgcn_mfma_f32_16x16x32_bf16(Bt[n][k], At[m][k], acc[ai][bj][m][n], 0, 0, 0); if (GEMM_PRIO_MODE == 0) __builtin_amdgcn_s_setprio(0); } while (0)
; #define PG8_WAIT_V(n) asm volatile("s_waitcnt vmcnt(" #n ")" ::: "memory")
; #define PG8_WAIT_VR(n, nr, flag) asm volatile("s_cmp_eq_u32 %0, 0\n\ts_cbranch_scc1 .Lpg8s%=\n\ts_waitcnt vmcnt(" #nr ")\n\ts_branch .Lpg8d%=\n.Lpg8s%=:\n\ts_waitcnt vmcnt(" #n ")\n.Lpg8d%=:" :: "s"(flag) : "memory", "scc")
; #define PG8_WAIT_L(n) asm volatile("s_waitcnt lgkmcnt(" #n ")" ::: "memory")
; #define PG8_BAR __builtin_amdgcn_s_barrier()
; #define PG8_SCHED __builtin_amdgcn_sched_barrier(0)
;     ...
;             PG8_WAIT_VR(8, 24, relax); PG8_WAIT_L(0); PG8_BAR; PG8_MMA(1, 0, At, B0); PG8_MMA(1, 1, At, B1); PG8_BAR; PG8_SCHED;
;     ...
;             PG8_WAIT_V(8); PG8_WAIT_L(0); PG8_BAR; PG8_MMA(1, 0, At, B0); PG8_MMA(1, 1, At, B1); PG8_BAR; PG8_SCHED;
;     ...
;             PG8_LDB(B0, 1, 0); PG8_LDB(B1, 1, 1); PG8_SCHED; PG8_LDA(At, 1, 0); PG8_STAGEA(PG8_SA(0, 1), a2 + hstepA, voffA);
;             PG8_WAIT_V(8); PG8_WAIT_L(0); PG8_BAR; PG8_MMA(0, 0, At, B0); PG8_MMA(0, 1, At, B1); PG8_BAR; PG8_SCHED;
	v_mfma_f32_16x16x32_bf16 v[62:65], v[150:153], v[182:185], 0
	v_mfma_f32_16x16x32_bf16 v[58:61], v[158:161], v[182:185], 0
	v_mfma_f32_16x16x32_bf16 v[46:49], v[150:153], v[190:193], 0
	v_mfma_f32_16x16x32_bf16 v[42:45], v[158:161], v[190:193], 0
	v_mfma_f32_16x16x32_bf16 v[30:33], v[150:153], v[198:201], 0
	v_mfma_f32_16x16x32_bf16 v[26:29], v[158:161], v[198:201], 0
	v_mfma_f32_16x16x32_bf16 v[12:15], v[150:153], v[206:209], 0
	v_mfma_f32_16x16x32_bf16 v[8:11], v[158:161], v[206:209], 0
	v_mfma_f32_16x16x32_bf16 v[62:65], v[154:157], v[186:189], v[62:65]
	v_mfma_f32_16x16x32_bf16 v[58:61], v[162:165], v[186:189], v[58:61]
	v_mfma_f32_16x16x32_bf16 v[46:49], v[154:157], v[194:197], v[46:49]
	v_mfma_f32_16x16x32_bf16 v[42:45], v[162:165], v[194:197], v[42:45]
	v_mfma_f32_16x16x32_bf16 v[30:33], v[154:157], v[202:205], v[30:33]
	v_mfma_f32_16x16x32_bf16 v[26:29], v[162:165], v[202:205], v[26:29]
	v_mfma_f32_16x16x32_bf16 v[12:15], v[154:157], v[210:213], v[12:15]
	v_mfma_f32_16x16x32_bf16 v[8:11], v[162:165], v[210:213], v[8:11]
	v_mfma_f32_16x16x32_bf16 v[54:57], v[166:169], v[182:185], 0
	v_mfma_f32_16x16x32_bf16 v[50:53], v[174:177], v[182:185], 0
	v_mfma_f32_16x16x32_bf16 v[38:41], v[166:169], v[190:193], 0
	v_mfma_f32_16x16x32_bf16 v[34:37], v[174:177], v[190:193], 0
	v_mfma_f32_16x16x32_bf16 v[22:25], v[166:169], v[198:201], 0
	v_mfma_f32_16x16x32_bf16 v[18:21], v[174:177], v[198:201], 0
	v_mfma_f32_16x16x32_bf16 v[4:7], v[166:169], v[206:209], 0
	v_mfma_f32_16x16x32_bf16 v[0:3], v[174:177], v[206:209], 0
	v_mfma_f32_16x16x32_bf16 v[54:57], v[170:173], v[186:189], v[54:57]
	v_mfma_f32_16x16x32_bf16 v[50:53], v[178:181], v[186:189], v[50:53]
	v_mfma_f32_16x16x32_bf16 v[38:41], v[170:173], v[194:197], v[38:41]
	v_mfma_f32_16x16x32_bf16 v[34:37], v[178:181], v[194:197], v[34:37]
	v_mfma_f32_16x16x32_bf16 v[22:25], v[170:173], v[202:205], v[22:25]
	v_mfma_f32_16x16x32_bf16 v[18:21], v[178:181], v[202:205], v[18:21]
	v_mfma_f32_16x16x32_bf16 v[4:7], v[170:173], v[210:213], v[4:7]
	v_mfma_f32_16x16x32_bf16 v[0:3], v[178:181], v[210:213], v[0:3]
	s_barrier
	s_setprio 0
	s_add_i32 s95, 0, 0x18000
	v_add_u32_e32 v149, s95, v146
	s_add_i32 vcc_lo, 0, 0x1c000
	ds_read_b128 v[150:153], v149
	ds_read_b128 v[154:157], v149 offset:1024
	ds_read_b128 v[158:161], v149 offset:2048
	ds_read_b128 v[162:165], v149 offset:3072
	v_add_u32_e32 v149, vcc_lo, v146
	ds_read_b128 v[166:169], v149
	ds_read_b128 v[170:173], v149 offset:1024
	ds_read_b128 v[174:177], v149 offset:2048
	ds_read_b128 v[178:181], v149 offset:3072
	s_add_u32 s6, s42, 0x100000
	s_addc_u32 s7, s43, 0
	s_mov_b32 m0, s73
	v_lshl_add_u64 v[220:221], s[6:7], 0, v[136:137]
	ds_read_b128 v[182:185], v148 offset:32768
	ds_read_b128 v[186:189], v148 offset:33792
	ds_read_b128 v[190:193], v148 offset:34816
	ds_read_b128 v[194:197], v148 offset:35840
	ds_read_b128 v[198:201], v148 offset:36864
	ds_read_b128 v[202:205], v148 offset:37888
	ds_read_b128 v[206:209], v148 offset:38912
	ds_read_b128 v[210:213], v148 offset:39936
	global_load_lds_dwordx4 v[220:221], off
	v_lshl_add_u64 v[220:221], s[6:7], 0, v[132:133]
	s_mov_b32 m0, s82
	s_nop 0
	global_load_lds_dwordx4 v[220:221], off
	s_waitcnt vmcnt(8)
	s_waitcnt lgkmcnt(0)
	s_setprio 1
	s_barrier
	v_mfma_f32_16x16x32_bf16 v[126:129], v[150:153], v[182:185], v[126:129]
	v_mfma_f32_16x16x32_bf16 v[122:125], v[158:161], v[182:185], v[122:125]
	v_mfma_f32_16x16x32_bf16 v[110:113], v[150:153], v[190:193], v[110:113]
	v_mfma_f32_16x16x32_bf16 v[106:109], v[158:161], v[190:193], v[106:109]
	v_mfma_f32_16x16x32_bf16 v[94:97], v[150:153], v[198:201], v[94:97]
	v_mfma_f32_16x16x32_bf16 v[90:93], v[158:161], v[198:201], v[90:93]
	v_mfma_f32_16x16x32_bf16 v[78:81], v[150:153], v[206:209], v[78:81]
	v_mfma_f32_16x16x32_bf16 v[74:77], v[158:161], v[206:209], v[74:77]
	v_mfma_f32_16x16x32_bf16 v[126:129], v[154:157], v[186:189], v[126:129]
	v_mfma_f32_16x16x32_bf16 v[122:125], v[162:165], v[186:189], v[122:125]
	v_mfma_f32_16x16x32_bf16 v[110:113], v[154:157], v[194:197], v[110:113]
	v_mfma_f32_16x16x32_bf16 v[106:109], v[162:165], v[194:197], v[106:109]
	v_mfma_f32_16x16x32_bf16 v[94:97], v[154:157], v[202:205], v[94:97]
	v_mfma_f32_16x16x32_bf16 v[90:93], v[162:165], v[202:205], v[90:93]
	v_mfma_f32_16x16x32_bf16 v[78:81], v[154:157], v[210:213], v[78:81]
	v_mfma_f32_16x16x32_bf16 v[74:77], v[162:165], v[210:213], v[74:77]
	v_mfma_f32_16x16x32_bf16 v[118:121], v[166:169], v[182:185], v[118:121]
	v_mfma_f32_16x16x32_bf16 v[114:117], v[174:177], v[182:185], v[114:117]
	v_mfma_f32_16x16x32_bf16 v[102:105], v[166:169], v[190:193], v[102:105]
	v_mfma_f32_16x16x32_bf16 v[98:101], v[174:177], v[190:193], v[98:101]
	v_mfma_f32_16x16x32_bf16 v[86:89], v[166:169], v[198:201], v[86:89]
	v_mfma_f32_16x16x32_bf16 v[82:85], v[174:177], v[198:201], v[82:85]
	v_mfma_f32_16x16x32_bf16 v[70:73], v[166:169], v[206:209], v[70:73]
	v_mfma_f32_16x16x32_bf16 v[66:69], v[174:177], v[206:209], v[66:69]
	v_mfma_f32_16x16x32_bf16 v[118:121], v[170:173], v[186:189], v[118:121]
	v_mfma_f32_16x16x32_bf16 v[114:117], v[178:181], v[186:189], v[114:117]
	v_mfma_f32_16x16x32_bf16 v[102:105], v[170:173], v[194:197], v[102:105]
	v_mfma_f32_16x16x32_bf16 v[98:101], v[178:181], v[194:197], v[98:101]
	v_mfma_f32_16x16x32_bf16 v[86:89], v[170:173], v[202:205], v[86:89]
	v_mfma_f32_16x16x32_bf16 v[82:85], v[178:181], v[202:205], v[82:85]
	v_mfma_f32_16x16x32_bf16 v[70:73], v[170:173], v[210:213], v[70:73]
	v_mfma_f32_16x16x32_bf16 v[66:69], v[178:181], v[210:213], v[66:69]
	s_barrier
; #define PG8_STAGEA(bufoff, gbase, voff) PG8_STAGE_X(bufoff, gbase, voff, AUXA)
; #define PG8_STAGEB(bufoff, gbase, voff) PG8_STAGE_X(bufoff, gbase, voff, AUXB)
; #define PG8_LDA(dst, b, h) do { _Pragma("unroll") for (int m = 0; m < 4; ++m) _Pragma("unroll") for (int k = 0; k < 2; ++k) dst[m][k] = *(const PG8_LAS bf16x8*)(lds + PG8_SA(b, h) + aoff + m * 2048 + k * 1024); } while (0)
; #define PG8_MMA(ai, bj, At, Bt) do { if (GEMM_PRIO_MODE == 0) __builtin_amdgcn_s_setprio(1); PG8_MMA_LOOPS \
;         acc[ai][bj][m][n] = __builtin_amdgcn_mfma_f32_16x16x32_bf16(Bt[n][k], At[m][k], acc[ai][bj][m][n], 0, 0, 0); if (GEMM_PRIO_MODE == 0) __builtin_amdgcn_s_setprio(0); } while (0)
; #define PG8_WAIT_V(n) asm volatile("s_waitcnt vmcnt(" #n ")" ::: "memory")
; #define PG8_WAIT_L(n) asm volatile("s_waitcnt lgkmcnt(" #n ")" ::: "memory")
; #define PG8_BAR __builtin_amdgcn_s_barrier()
; #define PG8_SCHED __builtin_amdgcn_sched_barrier(0)
;     ...
;             PG8_LDA(At, 1, 1); PG8_STAGEB(PG8_SB(1, 0), b3, voffB); PG8_STAGEB(PG8_SB(1, 1), b3 + hstepB, voffB); PG8_STAGEA(PG8_SA(1, 0), a3, voffA);
;             PG8_WAIT_V(8); PG8_WAIT_L(0); PG8_BAR; PG8_MMA(1, 0, At, B0); PG8_MMA(1, 1, At, B1); PG8_BAR; PG8_SCHED;
	s_setprio 0
	s_add_i32 s6, s95, s50
	v_lshl_add_u64 v[144:145], v[144:145], 0, s[86:87]
	s_mov_b32 m0, s6
	ds_read_b128 v[182:185], v148 offset:49152
	ds_read_b128 v[186:189], v148 offset:50176
	ds_read_b128 v[190:193], v148 offset:51200
	ds_read_b128 v[194:197], v148 offset:52224
	ds_read_b128 v[198:201], v148 offset:53248
	ds_read_b128 v[202:205], v148 offset:54272
	ds_read_b128 v[206:209], v148 offset:55296
	ds_read_b128 v[210:213], v148 offset:56320
	global_load_lds_dwordx4 v[144:145], off
	s_add_i32 m0, s6, 0x2000
	s_add_u32 s6, s16, 0x100080
	v_lshl_add_u64 v[144:145], v[214:215], 0, s[86:87]
	s_addc_u32 s7, s17, 0
	s_add_i32 s16, vcc_lo, s50
	global_load_lds_dwordx4 v[144:145], off
	v_lshl_add_u64 v[144:145], s[6:7], 0, v[134:135]
	s_mov_b32 m0, s16
	s_nop 0
	global_load_lds_dwordx4 v[144:145], off
	v_lshl_add_u64 v[144:145], s[6:7], 0, v[130:131]
	s_add_i32 m0, s16, 0x2000
	s_nop 0
	global_load_lds_dwordx4 v[144:145], off
	v_lshl_add_u64 v[144:145], v[216:217], 0, s[86:87]
	s_mov_b32 m0, s83
	s_nop 0
	global_load_lds_dwordx4 v[144:145], off
	v_lshl_add_u64 v[144:145], v[218:219], 0, s[86:87]
	s_mov_b32 m0, s90
	s_nop 0
	global_load_lds_dwordx4 v[144:145], off
	s_waitcnt vmcnt(8)
	s_waitcnt lgkmcnt(0)
	s_nop 0
	s_setprio 1
	s_barrier
	v_mfma_f32_16x16x32_bf16 v[62:65], v[150:153], v[182:185], v[62:65]
	v_mfma_f32_16x16x32_bf16 v[58:61], v[158:161], v[182:185], v[58:61]
	v_mfma_f32_16x16x32_bf16 v[46:49], v[150:153], v[190:193], v[46:49]
	v_mfma_f32_16x16x32_bf16 v[42:45], v[158:161], v[190:193], v[42:45]
	v_mfma_f32_16x16x32_bf16 v[30:33], v[150:153], v[198:201], v[30:33]
	v_mfma_f32_16x16x32_bf16 v[26:29], v[158:161], v[198:201], v[26:29]
	v_mfma_f32_16x16x32_bf16 v[12:15], v[150:153], v[206:209], v[12:15]
	v_mfma_f32_16x16x32_bf16 v[8:11], v[158:161], v[206:209], v[8:11]
	v_mfma_f32_16x16x32_bf16 v[62:65], v[154:157], v[186:189], v[62:65]
	v_mfma_f32_16x16x32_bf16 v[58:61], v[162:165], v[186:189], v[58:61]
	v_mfma_f32_16x16x32_bf16 v[46:49], v[154:157], v[194:197], v[46:49]
	v_mfma_f32_16x16x32_bf16 v[42:45], v[162:165], v[194:197], v[42:45]
	v_mfma_f32_16x16x32_bf16 v[30:33], v[154:157], v[202:205], v[30:33]
	v_mfma_f32_16x16x32_bf16 v[26:29], v[162:165], v[202:205], v[26:29]
	v_mfma_f32_16x16x32_bf16 v[12:15], v[154:157], v[210:213], v[12:15]
	v_mfma_f32_16x16x32_bf16 v[8:11], v[162:165], v[210:213], v[8:11]
	v_mfma_f32_16x16x32_bf16 v[54:57], v[166:169], v[182:185], v[54:57]
	v_mfma_f32_16x16x32_bf16 v[50:53], v[174:177], v[182:185], v[50:53]
	v_mfma_f32_16x16x32_bf16 v[38:41], v[166:169], v[190:193], v[38:41]
	v_mfma_f32_16x16x32_bf16 v[34:37], v[174:177], v[190:193], v[34:37]
	v_mfma_f32_16x16x32_bf16 v[22:25], v[166:169], v[198:201], v[22:25]
	v_mfma_f32_16x16x32_bf16 v[18:21], v[174:177], v[198:201], v[18:21]
	v_mfma_f32_16x16x32_bf16 v[4:7], v[166:169], v[206:209], v[4:7]
	v_mfma_f32_16x16x32_bf16 v[0:3], v[174:177], v[206:209], v[0:3]
	v_mfma_f32_16x16x32_bf16 v[54:57], v[170:173], v[186:189], v[54:57]
	v_mfma_f32_16x16x32_bf16 v[50:53], v[178:181], v[186:189], v[50:53]
	v_mfma_f32_16x16x32_bf16 v[38:41], v[170:173], v[194:197], v[38:41]
	v_mfma_f32_16x16x32_bf16 v[34:37], v[178:181], v[194:197], v[34:37]
	v_mfma_f32_16x16x32_bf16 v[22:25], v[170:173], v[202:205], v[22:25]
	v_mfma_f32_16x16x32_bf16 v[18:21], v[178:181], v[202:205], v[18:21]
	v_mfma_f32_16x16x32_bf16 v[4:7], v[170:173], v[210:213], v[4:7]
	v_mfma_f32_16x16x32_bf16 v[0:3], v[178:181], v[210:213], v[0:3]
	s_barrier
	s_setprio 0
	s_add_i32 s39, s39, 2
	s_add_u32 s40, s40, 0x100
	s_addc_u32 s41, s41, 0
	s_add_u32 s12, s12, 0x100
	s_addc_u32 s13, s13, 0
	v_add_u32_e32 v222, 0x10000, v146
